# v41 + phase B prologue: first x row loads issued before gate-weight staging; 8 serialized staging loads batched with counted vmcnt
# speedup vs baseline: 1.0022x; 1.0022x over previous
.LBB0_114:
	s_or_b64 exec, exec, s[26:27]
	v_lshl_add_u32 v106, s2, 6, v86
	v_ashrrev_i32_e32 v107, 31, v106
	v_lshlrev_b64 v[106:107], 13, v[106:107]
	v_lshl_add_u64 v[106:107], v[70:71], 0, v[106:107]
	global_load_dwordx4 v[60:63], v[106:107], off nt
	global_load_dwordx4 v[56:59], v[106:107], off offset:1024 nt
	global_load_dwordx4 v[52:55], v[106:107], off offset:2048 nt
	global_load_dwordx4 v[48:51], v[106:107], off offset:3072 nt
	v_add_co_u32_e32 v106, vcc, 0x1000, v106
	s_nop 1
	v_addc_co_u32_e32 v107, vcc, 0, v107, vcc
	global_load_dwordx4 v[44:47], v[106:107], off nt
	global_load_dwordx4 v[40:43], v[106:107], off offset:1024 nt
	global_load_dwordx4 v[36:39], v[106:107], off offset:2048 nt
	global_load_dwordx4 v[32:35], v[106:107], off offset:3072 nt
	s_and_saveexec_b64 s[26:27], s[4:5]
	s_cbranch_execz .LBB0_117
	s_mov_b32 s3, 0xd020
	v_add_u32_e32 v101, 0x0, v64
	v_ashrrev_i32_e32 v150, 1, v101
	v_lshlrev_b32_e32 v102, 2, v101
	v_and_b32_e32 v102, 4, v102
	v_mov_b64_e32 v[104:105], s[70:71]
	v_mad_i64_i32 v[104:105], s[36:37], v150, s3, v[104:105]
	v_lshlrev_b32_e32 v66, 2, v102
	v_lshl_add_u64 v[104:105], v[104:105], 0, v[66:67]
	v_add_co_u32_e32 v104, vcc, 0x9000, v104
	v_lshlrev_b32_e32 v150, 2, v150
	v_lshlrev_b32_e32 v102, 13, v102
	v_addc_co_u32_e32 v105, vcc, 0, v105, vcc
	global_load_dwordx4 v[110:113], v[104:105], off
	v_add3_u32 v150, 0, v150, v102
	v_add_u32_e32 v101, 0x200, v64
	v_ashrrev_i32_e32 v151, 1, v101
	v_lshlrev_b32_e32 v102, 2, v101
	v_and_b32_e32 v102, 4, v102
	v_mov_b64_e32 v[104:105], s[70:71]
	v_mad_i64_i32 v[104:105], s[36:37], v151, s3, v[104:105]
	v_lshlrev_b32_e32 v66, 2, v102
	v_lshl_add_u64 v[104:105], v[104:105], 0, v[66:67]
	v_add_co_u32_e32 v104, vcc, 0x9000, v104
	v_lshlrev_b32_e32 v151, 2, v151
	v_lshlrev_b32_e32 v102, 13, v102
	v_addc_co_u32_e32 v105, vcc, 0, v105, vcc
	global_load_dwordx4 v[114:117], v[104:105], off
	v_add3_u32 v151, 0, v151, v102
	v_add_u32_e32 v101, 0x400, v64
	v_ashrrev_i32_e32 v152, 1, v101
	v_lshlrev_b32_e32 v102, 2, v101
	v_and_b32_e32 v102, 4, v102
	v_mov_b64_e32 v[104:105], s[70:71]
	v_mad_i64_i32 v[104:105], s[36:37], v152, s3, v[104:105]
	v_lshlrev_b32_e32 v66, 2, v102
	v_lshl_add_u64 v[104:105], v[104:105], 0, v[66:67]
	v_add_co_u32_e32 v104, vcc, 0x9000, v104
	v_lshlrev_b32_e32 v152, 2, v152
	v_lshlrev_b32_e32 v102, 13, v102
	v_addc_co_u32_e32 v105, vcc, 0, v105, vcc
	global_load_dwordx4 v[118:121], v[104:105], off
	v_add3_u32 v152, 0, v152, v102
	v_add_u32_e32 v101, 0x600, v64
	v_ashrrev_i32_e32 v153, 1, v101
	v_lshlrev_b32_e32 v102, 2, v101
	v_and_b32_e32 v102, 4, v102
	v_mov_b64_e32 v[104:105], s[70:71]
	v_mad_i64_i32 v[104:105], s[36:37], v153, s3, v[104:105]
	v_lshlrev_b32_e32 v66, 2, v102
	v_lshl_add_u64 v[104:105], v[104:105], 0, v[66:67]
	v_add_co_u32_e32 v104, vcc, 0x9000, v104
	v_lshlrev_b32_e32 v153, 2, v153
	v_lshlrev_b32_e32 v102, 13, v102
	v_addc_co_u32_e32 v105, vcc, 0, v105, vcc
	global_load_dwordx4 v[122:125], v[104:105], off
	v_add3_u32 v153, 0, v153, v102
	v_add_u32_e32 v101, 0x800, v64
	v_ashrrev_i32_e32 v154, 1, v101
	v_lshlrev_b32_e32 v102, 2, v101
	v_and_b32_e32 v102, 4, v102
	v_mov_b64_e32 v[104:105], s[70:71]
	v_mad_i64_i32 v[104:105], s[36:37], v154, s3, v[104:105]
	v_lshlrev_b32_e32 v66, 2, v102
	v_lshl_add_u64 v[104:105], v[104:105], 0, v[66:67]
	v_add_co_u32_e32 v104, vcc, 0x9000, v104
	v_lshlrev_b32_e32 v154, 2, v154
	v_lshlrev_b32_e32 v102, 13, v102
	v_addc_co_u32_e32 v105, vcc, 0, v105, vcc
	global_load_dwordx4 v[126:129], v[104:105], off
	v_add3_u32 v154, 0, v154, v102
	v_add_u32_e32 v101, 0xa00, v64
	v_ashrrev_i32_e32 v155, 1, v101
	v_lshlrev_b32_e32 v102, 2, v101
	v_and_b32_e32 v102, 4, v102
	v_mov_b64_e32 v[104:105], s[70:71]
	v_mad_i64_i32 v[104:105], s[36:37], v155, s3, v[104:105]
	v_lshlrev_b32_e32 v66, 2, v102
	v_lshl_add_u64 v[104:105], v[104:105], 0, v[66:67]
	v_add_co_u32_e32 v104, vcc, 0x9000, v104
	v_lshlrev_b32_e32 v155, 2, v155
	v_lshlrev_b32_e32 v102, 13, v102
	v_addc_co_u32_e32 v105, vcc, 0, v105, vcc
	global_load_dwordx4 v[130:133], v[104:105], off
	v_add3_u32 v155, 0, v155, v102
	v_add_u32_e32 v101, 0xc00, v64
	v_ashrrev_i32_e32 v156, 1, v101
	v_lshlrev_b32_e32 v102, 2, v101
	v_and_b32_e32 v102, 4, v102
	v_mov_b64_e32 v[104:105], s[70:71]
	v_mad_i64_i32 v[104:105], s[36:37], v156, s3, v[104:105]
	v_lshlrev_b32_e32 v66, 2, v102
	v_lshl_add_u64 v[104:105], v[104:105], 0, v[66:67]
	v_add_co_u32_e32 v104, vcc, 0x9000, v104
	v_lshlrev_b32_e32 v156, 2, v156
	v_lshlrev_b32_e32 v102, 13, v102
	v_addc_co_u32_e32 v105, vcc, 0, v105, vcc
	global_load_dwordx4 v[134:137], v[104:105], off
	v_add3_u32 v156, 0, v156, v102
	v_add_u32_e32 v101, 0xe00, v64
	v_ashrrev_i32_e32 v157, 1, v101
	v_lshlrev_b32_e32 v102, 2, v101
	v_and_b32_e32 v102, 4, v102
	v_mov_b64_e32 v[104:105], s[70:71]
	v_mad_i64_i32 v[104:105], s[36:37], v157, s3, v[104:105]
	v_lshlrev_b32_e32 v66, 2, v102
	v_lshl_add_u64 v[104:105], v[104:105], 0, v[66:67]
	v_add_co_u32_e32 v104, vcc, 0x9000, v104
	v_lshlrev_b32_e32 v157, 2, v157
	v_lshlrev_b32_e32 v102, 13, v102
	v_addc_co_u32_e32 v105, vcc, 0, v105, vcc
	global_load_dwordx4 v[138:141], v[104:105], off
	v_add3_u32 v157, 0, v157, v102
	s_waitcnt vmcnt(7)
	ds_write2st64_b32 v150, v110, v111 offset0:64 offset1:96
	ds_write2st64_b32 v150, v112, v113 offset0:128 offset1:160
	s_waitcnt vmcnt(6)
	ds_write2st64_b32 v151, v114, v115 offset0:64 offset1:96
	ds_write2st64_b32 v151, v116, v117 offset0:128 offset1:160
	s_waitcnt vmcnt(5)
	ds_write2st64_b32 v152, v118, v119 offset0:64 offset1:96
	ds_write2st64_b32 v152, v120, v121 offset0:128 offset1:160
	s_waitcnt vmcnt(4)
	ds_write2st64_b32 v153, v122, v123 offset0:64 offset1:96
	ds_write2st64_b32 v153, v124, v125 offset0:128 offset1:160
	s_waitcnt vmcnt(3)
	ds_write2st64_b32 v154, v126, v127 offset0:64 offset1:96
	ds_write2st64_b32 v154, v128, v129 offset0:128 offset1:160
	s_waitcnt vmcnt(2)
	ds_write2st64_b32 v155, v130, v131 offset0:64 offset1:96
	ds_write2st64_b32 v155, v132, v133 offset0:128 offset1:160
	s_waitcnt vmcnt(1)
	ds_write2st64_b32 v156, v134, v135 offset0:64 offset1:96
	ds_write2st64_b32 v156, v136, v137 offset0:128 offset1:160
	s_waitcnt vmcnt(0)
	ds_write2st64_b32 v157, v138, v139 offset0:64 offset1:96
	ds_write2st64_b32 v157, v140, v141 offset0:128 offset1:160
.LBB0_117:
	s_or_b64 exec, exec, s[26:27]
	s_waitcnt lgkmcnt(0)
	s_barrier
	v_ashrrev_i32_e32 v81, 31, v80
	v_lshlrev_b64 v[0:1], 13, v[80:81]
	v_lshl_add_u64 v[84:85], v[70:71], 0, v[0:1]
	s_mov_b64 s[26:27], 0
	v_mov_b32_e32 v82, v80
	s_waitcnt vmcnt(7)
	v_mov_b64_e32 v[0:1], v[60:61]
	s_waitcnt vmcnt(6)
	v_mov_b64_e32 v[4:5], v[56:57]
	s_waitcnt vmcnt(5)
	v_mov_b64_e32 v[8:9], v[52:53]
	s_waitcnt vmcnt(4)
	v_mov_b64_e32 v[12:13], v[48:49]
	v_mov_b64_e32 v[2:3], v[62:63]
	v_mov_b64_e32 v[6:7], v[58:59]
	s_waitcnt vmcnt(3)
	v_mov_b64_e32 v[16:17], v[44:45]
	s_waitcnt vmcnt(2)
	v_mov_b64_e32 v[20:21], v[40:41]
	s_waitcnt vmcnt(1)
	v_mov_b64_e32 v[24:25], v[36:37]
	s_waitcnt vmcnt(0)
	v_mov_b64_e32 v[28:29], v[32:33]
	v_mov_b64_e32 v[10:11], v[54:55]
	v_mov_b64_e32 v[14:15], v[50:51]
	v_mov_b64_e32 v[18:19], v[46:47]
	v_mov_b64_e32 v[22:23], v[42:43]
	v_mov_b64_e32 v[26:27], v[38:39]
	v_mov_b64_e32 v[30:31], v[34:35]
	s_branch .LBB0_119
